# v57 with the static first mixer ticket chosen per blockIdx so that each XCD (round-robin placement) works on one (batch, kv head) K/V set in the first GQA round
# speedup vs baseline: 1.0058x; 1.0054x over previous
; #define LAS __attribute__((address_space(3)))
; __device__ __forceinline__ int opaque_tid() { int t; asm volatile("v_mov_b32 %0, %1" : "=v"(t) : "v"((int)threadIdx.x)); return t; }
; __global__ void __launch_bounds__(NTHREADS, 2) mega_fwd(Params P) {
;     ...
;         {
;             LAS int* qslot = (LAS int*)(ldsl + RING_BYTES + 1024);
;             const int n_gqa = 384, n_na = 384, n_sg = 132, n_cx = lastl ? 0 : 24;
;             const int n_prod = n_gqa + n_na + n_sg + n_cx;
;             const int ntot = n_prod + 256 + (lastl ? 0 : 24);
;             unsigned* cw = ctl + CW_DEP + (size_t)l * 66 * 16;
;             for (;;) {
;                 if (opaque_tid() == 0) qslot[0] = (int)atomicAdd(ctl + 64 * (l + 1), 1u);
;                 __syncthreads();
;                 const int idx = __builtin_amdgcn_readfirstlane(qslot[0]);
;                 __syncthreads();
;                 if (idx >= ntot) break;
;                 if (idx < n_gqa) {
;                     const int qb = idx / 12, r12 = idx % 12, b = r12 / 6, h = r12 % 6; const size_t rb = (size_t)b * RPB;
;                     ap::unit<8, 0>(qkv + (rb + 256 * qb) * DIN + C_QC + 64 * h, qkv + rb * DIN + C_KC + 64 * (h / 3), qkv + rb * DIN + C_VC + 64 * (h / 3),
;                                    omix + (rb + 256 * qb) * DM + 640 + 64 * h, ssb + (rb + 256 * qb) * 4 + 2, 132, (char*)lds, 0, 0, tcos[4096 + l]);
.LBB0_437:
	s_or_b64 exec, exec, s[34:35]
	v_readlane_b32 s0, v252, 11
	v_readlane_b32 s1, v252, 12
	s_and_b64 s[0:1], s[0:1], exec
	s_cselect_b32 s0, 24, 0
	s_or_b32 s1, s0, 0x384
	v_writelane_b32 v252, s1, 15
	s_lshl_b32 s0, s0, 1
	s_or_b32 s52, s0, 0x484
	s_mov_b64 s[0:1], s[76:77]
	v_readlane_b32 s20, v252, 9
	s_waitcnt lgkmcnt(0)
	s_barrier
	s_mul_i32 s3, s20, 0x1080
	s_mul_hi_u32 s2, s20, 0x1080
	s_add_u32 s0, s0, s3
	s_addc_u32 s1, s1, s2
	v_readlane_b32 s21, v252, 10
	s_add_u32 s53, s0, 0x8000
	s_addc_u32 s54, s1, 0
	s_lshl_b64 s[0:1], s[20:21], 21
	v_writelane_b32 v252, s0, 16
	s_lshl_b32 s86, s20, 8
	v_readlane_b32 s4, v253, 25
	v_writelane_b32 v252, s1, 17
	s_lshl_b64 s[0:1], s[20:21], 17
	s_lshl_b64 s[2:3], s[86:87], 2
	v_readlane_b32 s8, v253, 29
	v_readlane_b32 s9, v253, 30
	s_add_u32 s2, s8, s2
	s_addc_u32 s3, s9, s3
	v_writelane_b32 v252, s2, 18
	v_readlane_b32 s6, v253, 27
	v_readlane_b32 s7, v253, 28
	v_writelane_b32 v252, s3, 19
	v_readlane_b32 s2, v254, 10
	s_add_u32 s0, s2, s0
	v_writelane_b32 v252, s0, 20
	v_readlane_b32 s0, v254, 11
	s_addc_u32 s0, s0, s1
	v_readlane_b32 s5, v253, 26
	v_writelane_b32 v252, s0, 21
	s_lshl_b64 s[0:1], s[20:21], 11
	s_add_u32 s0, s6, s0
	v_writelane_b32 v252, s0, 22
	s_addc_u32 s0, s7, s1
	v_writelane_b32 v252, s0, 23
	v_writelane_b32 v252, s52, 24
	v_writelane_b32 v252, s53, 25
	v_readlane_b32 s10, v253, 31
	v_readlane_b32 s11, v253, 32
	v_readlane_b32 s12, v253, 33
	v_readlane_b32 s13, v253, 34
	v_readlane_b32 s14, v253, 35
	v_readlane_b32 s15, v253, 36
	v_readlane_b32 s16, v253, 37
	v_readlane_b32 s17, v253, 38
	v_readlane_b32 s18, v253, 39
	v_readlane_b32 s19, v253, 40
	v_writelane_b32 v252, s54, 26
	s_mov_b32 s101, 0
	v_readlane_b32 s100, v254, 57
	s_nop 3
	s_and_b32 s0, s100, 7
	s_lshr_b32 s1, s100, 3
	s_and_b32 s2, s0, 3
	s_lshr_b32 s0, s0, 2
	s_lshl_b32 s0, s0, 5
	s_add_i32 s0, s0, s1
	s_mul_hi_u32 s1, s0, 0xaaaaaaab
	s_lshr_b32 s1, s1, 1
	s_mul_i32 s3, s1, 3
	s_sub_i32 s3, s0, s3
	s_mul_i32 s1, s1, 12
	s_mul_i32 s0, s2, 3
	s_add_i32 s1, s1, s0
	s_add_i32 s100, s1, s3
	s_cmp_gt_u32 s100, 0xff
	s_cbranch_scc0 .Lsf_ok
	s_add_i32 s100, s2, 251
.Lsf_ok:
	s_sub_i32 s100, s100, 0x100
	v_mov_b32_e32 v0, s100
	s_mov_b32 s101, 1
	s_branch .LBB0_441
